# top-k selection by wave-level quickselect on the unique 64-bit keys (ballot + popcount per pivot) instead of full pairwise ranking; same selected set
# speedup vs baseline: 1.0061x; 1.0061x over previous
.LBB0_1297:
	s_add_i32 s7, s6, s77
	s_mul_i32 s16, s7, 0x104
	v_add_u32_e32 v35, s16, v34
	ds_read2st64_b32 v[36:37], v35 offset1:65
	s_mov_b32 s24, 0
	s_waitcnt lgkmcnt(0)
	v_add_f32_e32 v38, v36, v37
	ds_read2st64_b32 v[36:37], v35 offset0:130 offset1:195
	s_waitcnt lgkmcnt(0)
	v_add_f32_e32 v35, v38, v36
	v_add_f32_e32 v35, v35, v37
	v_mov_b32_e32 v36, 0x461c4000
	v_cndmask_b32_e64 v35, v35, v36, s[10:11]
	v_mov_b32_e32 v36, 0
	v_cndmask_b32_e64 v39, v35, v36, s[12:13]
	v_sub_u32_e32 v38, 63, v0
	v_mov_b32_e32 v36, 0
	s_mov_b64 s[20:21], s[14:15]
.LBB0_1298:
	s_ff1_i32_b64 s24, s[20:21]
	v_readlane_b32 s19, v39, s24
	s_sub_i32 s18, 63, s24
	s_lshl_b64 s[96:97], 1, s24
	v_cmp_lt_u64_e64 s[16:17], s[18:19], v[38:39]
	s_nop 0
	s_bcnt1_i32_b64 s78, s[16:17]
	s_cmp_eq_u32 s78, 15
	s_cbranch_scc1 .Ltk_done
	s_cmp_gt_u32 s78, 15
	s_cbranch_scc1 .Ltk_up
	s_or_b64 s[96:97], s[96:97], s[16:17]
	s_andn2_b64 s[20:21], s[20:21], s[96:97]
	s_branch .LBB0_1298
.Ltk_up:
	s_and_b64 s[20:21], s[20:21], s[16:17]
	s_branch .LBB0_1298
.Ltk_done:
	s_or_b64 s[16:17], s[16:17], s[96:97]
	s_and_b64 s[16:17], s[16:17], s[14:15]
	s_and_saveexec_b64 s[18:19], vcc
	s_cbranch_execz .LBB0_1296
	s_lshl_b32 s7, s7, 3
	s_add_i32 s7, s7, 0
	s_add_i32 s7, s7, 0x10800
	v_mov_b32_e32 v35, s7
	v_mov_b64_e32 v[36:37], s[16:17]
	ds_write_b64 v35, v[36:37]
	s_branch .LBB0_1296
